# v39 + nt hint on the Up-GEMM hidden-activation (H) stores
# baseline (speedup 1.0000x reference)
; __device__ __forceinline__ unsigned cvt_pk_bf16(float lo, float hi) { unsigned r; asm volatile("v_cvt_pk_bf16_f32 %0, %1, %2" : "=v"(r) : "v"(lo), "v"(hi)); return r; }
; __device__ __forceinline__ int lane_id_v() { int l; asm volatile("v_mbcnt_lo_u32_b32 %0, -1, 0\n\tv_mbcnt_hi_u32_b32 %0, -1, %0" : "=v"(l)); return l; }
; #define LAS __attribute__((address_space(3)))
;     __device__ __forceinline__ void operator()(const f32x4 (&acc)[2][2][4][2], const pg8::Unit& u, int wr, int wc, int fr_, int fq_) const {
;         const int lane_ = pg8::lane_id_v(); const int fr = lane_ & 15, fq = lane_ >> 4;
;         const int lrow0 = u.pm * 256 + wr * 64 + fr;
;         const int b = batch_of(rowbase + u.pm * 256);
;         f32x4 sv[2][2];
; #pragma unroll
;         for (int bj = 0; bj < 2; ++bj)
; #pragma unroll
;             for (int n = 0; n < 2; ++n) sv[bj][n] = *(const LAS f32x4*)(xl + 16384 + (bj * 128 + wc * 32 + 8 * fq + 4 * n) * 4);
;         float rs8[8]; rows_rstd8_lds(xl, wr * 64 + fr, fq, rs8);
;         const int hcol = u.pn * 128 + wc * 32 + 8 * fq;
; #pragma unroll
;         for (int ai = 0; ai < 2; ++ai)
; #pragma unroll
;             for (int m = 0; m < 4; ++m) {
;                 const int lr = lrow0 + ai * 128 + m * 16;
;                 const float rs = rs8[ai * 4 + m];
;                 const f32x4 g0 = acc[ai][0][m][0] * rs + sv[0][0], g1 = acc[ai][0][m][1] * rs + sv[0][1];
;                 const f32x4 u0 = acc[ai][1][m][0] * rs + sv[1][0], u1 = acc[ai][1][m][1] * rs + sv[1][1];
;                 const f32x2 ha = pg8::silu_mul_pk((f32x2){g0[0], g0[1]}, (f32x2){u0[0], u0[1]}), hb = pg8::silu_mul_pk((f32x2){g0[2], g0[3]}, (f32x2){u0[2], u0[3]});
;                 const f32x2 hc = pg8::silu_mul_pk((f32x2){g1[0], g1[1]}, (f32x2){u1[0], u1[1]}), hd = pg8::silu_mul_pk((f32x2){g1[2], g1[3]}, (f32x2){u1[2], u1[3]});
;                 u32x4 w; w.x = cvt_pk_bf16(ha.x, ha.y); w.y = cvt_pk_bf16(hb.x, hb.y); w.z = cvt_pk_bf16(hc.x, hc.y); w.w = cvt_pk_bf16(hd.x, hd.y);
.LBB0_379:
	v_mbcnt_lo_u32_b32 v228, -1, 0
	v_mbcnt_hi_u32_b32 v228, -1, v228
	v_and_b32_e32 v224, 15, v228
	v_add_u32_e32 v224, s91, v224
	v_lshlrev_b32_e32 v224, 2, v224
	v_add_u32_e32 v224, 0x26800, v224
	ds_read_b32 v208, v224
	ds_read_b32 v209, v224 offset:64
	ds_read_b32 v210, v224 offset:128
	ds_read_b32 v211, v224 offset:192
	ds_read_b32 v212, v224 offset:512
	ds_read_b32 v213, v224 offset:576
	ds_read_b32 v214, v224 offset:640
	ds_read_b32 v215, v224 offset:704
	s_waitcnt lgkmcnt(0)
	v_mbcnt_lo_u32_b32 v158, -1, 0
	v_mbcnt_hi_u32_b32 v158, -1, v158
	s_add_i32 s23, s23, s91
	v_and_b32_e32 v159, 15, v158
	v_or_b32_e32 v165, s23, v159
	v_ashrrev_i32_e32 v167, 4, v158
	v_readlane_b32 s26, v252, 22
	s_add_i32 s23, 0, 0x22400
	v_lshl_add_u32 v80, v167, 5, s26
	ds_read_b128 v[92:95], v80
	ds_read_b128 v[88:91], v80 offset:16
	ds_read_b128 v[84:87], v80 offset:512
	ds_read_b128 v[80:83], v80 offset:528
	s_mov_b32 s26, 0x358637bd
	s_lshl_b32 s2, s2, 7
	s_waitcnt lgkmcnt(0)
	s_waitcnt lgkmcnt(0)
	s_or_b32 s2, s2, s15
	s_mov_b64 s[76:77], s[62:63]
	s_waitcnt lgkmcnt(0)
	s_waitcnt lgkmcnt(0)
	s_nop 0
	s_nop 0
	s_nop 0
	v_mov_b32_e32 v172, v208
	s_waitcnt lgkmcnt(0)
	v_mov_b32_e32 v170, v209
	v_pk_fma_f32 v[126:127], v[126:127], v[170:171], v[94:95] op_sel_hi:[1,0,1]
	v_pk_fma_f32 v[124:125], v[124:125], v[170:171], v[92:93] op_sel_hi:[1,0,1]
	s_waitcnt lgkmcnt(0)
	v_pk_fma_f32 v[116:117], v[116:117], v[170:171], v[84:85] op_sel_hi:[1,0,1]
	v_pk_fma_f32 v[118:119], v[118:119], v[170:171], v[86:87] op_sel_hi:[1,0,1]
	v_pk_mul_f32 v[116:117], v[124:125], v[116:117]
	v_pk_fma_f32 v[120:121], v[120:121], v[170:171], v[88:89] op_sel_hi:[1,0,1]
	s_waitcnt lgkmcnt(0)
	v_pk_mul_f32 v[118:119], v[126:127], v[118:119]
	v_pk_fma_f32 v[112:113], v[112:113], v[170:171], v[80:81] op_sel_hi:[1,0,1]
	v_pk_fma_f32 v[122:123], v[122:123], v[170:171], v[90:91] op_sel_hi:[1,0,1]
	v_pk_mul_f32 v[112:113], v[120:121], v[112:113]
	s_waitcnt lgkmcnt(0)
	v_pk_fma_f32 v[114:115], v[114:115], v[170:171], v[82:83] op_sel_hi:[1,0,1]
	v_pk_mul_f32 v[114:115], v[122:123], v[114:115]
	s_nop 0
	s_nop 0
	v_mov_b32_e32 v168, v210
	v_pk_fma_f32 v[110:111], v[110:111], v[168:169], v[94:95] op_sel_hi:[1,0,1]
	v_pk_fma_f32 v[108:109], v[108:109], v[168:169], v[92:93] op_sel_hi:[1,0,1]
	v_pk_fma_f32 v[100:101], v[100:101], v[168:169], v[84:85] op_sel_hi:[1,0,1]
	s_waitcnt lgkmcnt(0)
	v_mov_b32_e32 v166, v211
	v_pk_mul_f32 v[100:101], v[108:109], v[100:101]
	v_pk_fma_f32 v[102:103], v[102:103], v[168:169], v[86:87] op_sel_hi:[1,0,1]
	s_waitcnt lgkmcnt(0)
	v_pk_fma_f32 v[104:105], v[104:105], v[168:169], v[88:89] op_sel_hi:[1,0,1]
	v_pk_mul_f32 v[102:103], v[110:111], v[102:103]
	v_pk_fma_f32 v[96:97], v[96:97], v[168:169], v[80:81] op_sel_hi:[1,0,1]
	v_pk_fma_f32 v[106:107], v[106:107], v[168:169], v[90:91] op_sel_hi:[1,0,1]
	s_waitcnt lgkmcnt(0)
	v_pk_mul_f32 v[96:97], v[104:105], v[96:97]
	v_pk_fma_f32 v[98:99], v[98:99], v[168:169], v[82:83] op_sel_hi:[1,0,1]
	v_pk_fma_f32 v[78:79], v[78:79], v[166:167], v[94:95] op_sel_hi:[1,0,1]
	v_pk_mul_f32 v[98:99], v[106:107], v[98:99]
	s_waitcnt lgkmcnt(0)
	v_pk_fma_f32 v[76:77], v[76:77], v[166:167], v[92:93] op_sel_hi:[1,0,1]
	v_pk_fma_f32 v[68:69], v[68:69], v[166:167], v[84:85] op_sel_hi:[1,0,1]
	v_pk_mul_f32 v[68:69], v[76:77], v[68:69]
	v_pk_fma_f32 v[70:71], v[70:71], v[166:167], v[86:87] op_sel_hi:[1,0,1]
	v_pk_fma_f32 v[72:73], v[72:73], v[166:167], v[88:89] op_sel_hi:[1,0,1]
	v_pk_mul_f32 v[70:71], v[78:79], v[70:71]
	v_mov_b32_e32 v164, v212
	v_pk_fma_f32 v[64:65], v[64:65], v[166:167], v[80:81] op_sel_hi:[1,0,1]
	v_pk_fma_f32 v[74:75], v[74:75], v[166:167], v[90:91] op_sel_hi:[1,0,1]
	v_pk_mul_f32 v[64:65], v[72:73], v[64:65]
	s_waitcnt lgkmcnt(0)
	v_pk_fma_f32 v[142:143], v[142:143], v[172:173], v[94:95] op_sel_hi:[1,0,1]
	v_pk_fma_f32 v[140:141], v[140:141], v[172:173], v[92:93] op_sel_hi:[1,0,1]
	v_pk_fma_f32 v[132:133], v[132:133], v[172:173], v[84:85] op_sel_hi:[1,0,1]
	v_mov_b32_e32 v162, v213
	v_pk_fma_f32 v[138:139], v[138:139], v[172:173], v[90:91] op_sel_hi:[1,0,1]
	v_pk_fma_f32 v[136:137], v[136:137], v[172:173], v[88:89] op_sel_hi:[1,0,1]
	v_pk_fma_f32 v[134:135], v[134:135], v[172:173], v[86:87] op_sel_hi:[1,0,1]
	v_pk_fma_f32 v[128:129], v[128:129], v[172:173], v[80:81] op_sel_hi:[1,0,1]
	v_pk_fma_f32 v[130:131], v[130:131], v[172:173], v[82:83] op_sel_hi:[1,0,1]
	v_pk_mul_f32 v[172:173], v[140:141], s[88:89] op_sel_hi:[1,0]
	v_pk_mul_f32 v[132:133], v[140:141], v[132:133]
	v_pk_mul_f32 v[140:141], v[142:143], s[88:89] op_sel_hi:[1,0]
	s_waitcnt lgkmcnt(0)
	v_exp_f32_e32 v140, v140
	v_exp_f32_e32 v141, v141
	s_nop 0
	v_pk_add_f32 v[140:141], v[140:141], 1.0 op_sel_hi:[1,0]
	v_rcp_f32_e32 v140, v140
	v_rcp_f32_e32 v141, v141
	v_pk_mul_f32 v[134:135], v[142:143], v[134:135]
	v_exp_f32_e32 v172, v172
	v_pk_mul_f32 v[134:135], v[134:135], v[140:141]
	v_pk_mul_f32 v[140:141], v[136:137], s[88:89] op_sel_hi:[1,0]
	v_exp_f32_e32 v173, v173
	v_exp_f32_e32 v140, v140
	v_exp_f32_e32 v141, v141
	v_pk_mul_f32 v[128:129], v[136:137], v[128:129]
	v_pk_mul_f32 v[136:137], v[138:139], s[88:89] op_sel_hi:[1,0]
	s_waitcnt lgkmcnt(0)
	v_exp_f32_e32 v136, v136
	v_exp_f32_e32 v137, v137
	v_pk_add_f32 v[172:173], v[172:173], 1.0 op_sel_hi:[1,0]
	v_pk_add_f32 v[140:141], v[140:141], 1.0 op_sel_hi:[1,0]
	v_rcp_f32_e32 v172, v172
	v_rcp_f32_e32 v173, v173
	v_rcp_f32_e32 v140, v140
	v_rcp_f32_e32 v141, v141
	v_pk_add_f32 v[136:137], v[136:137], 1.0 op_sel_hi:[1,0]
	s_waitcnt lgkmcnt(0)
; __device__ __forceinline__ unsigned cvt_pk_bf16(float lo, float hi) { unsigned r; asm volatile("v_cvt_pk_bf16_f32 %0, %1, %2" : "=v"(r) : "v"(lo), "v"(hi)); return r; }
;     __device__ __forceinline__ void operator()(const f32x4 (&acc)[2][2][4][2], const pg8::Unit& u, int wr, int wc, int fr_, int fq_) const {
;     ...
;                 const int lr = lrow0 + ai * 128 + m * 16;
;                 const float rs = rs8[ai * 4 + m];
;                 const f32x4 g0 = acc[ai][0][m][0] * rs + sv[0][0], g1 = acc[ai][0][m][1] * rs + sv[0][1];
;                 const f32x4 u0 = acc[ai][1][m][0] * rs + sv[1][0], u1 = acc[ai][1][m][1] * rs + sv[1][1];
;                 const f32x2 ha = pg8::silu_mul_pk((f32x2){g0[0], g0[1]}, (f32x2){u0[0], u0[1]}), hb = pg8::silu_mul_pk((f32x2){g0[2], g0[3]}, (f32x2){u0[2], u0[3]});
;                 const f32x2 hc = pg8::silu_mul_pk((f32x2){g1[0], g1[1]}, (f32x2){u1[0], u1[1]}), hd = pg8::silu_mul_pk((f32x2){g1[2], g1[3]}, (f32x2){u1[2], u1[3]});
;                 u32x4 w; w.x = cvt_pk_bf16(ha.x, ha.y); w.y = cvt_pk_bf16(hb.x, hb.y); w.z = cvt_pk_bf16(hc.x, hc.y); w.w = cvt_pk_bf16(hd.x, hd.y);
;                 *(u32x4*)(H + (size_t)lr * FF + hcol) = w;
	v_rcp_f32_e32 v136, v136
	v_rcp_f32_e32 v137, v137
	v_lshl_add_u32 v174, v167, 3, s2
	v_pk_mul_f32 v[132:133], v[132:133], v[172:173]
	v_pk_mul_f32 v[130:131], v[138:139], v[130:131]
	v_pk_mul_f32 v[128:129], v[128:129], v[140:141]
	v_ashrrev_i32_e32 v175, 31, v174
	v_pk_mul_f32 v[130:131], v[130:131], v[136:137]
	v_cvt_pk_bf16_f32 v132, v132, v133
	v_cvt_pk_bf16_f32 v133, v134, v135
	v_cvt_pk_bf16_f32 v134, v128, v129
	v_mov_b64_e32 v[128:129], s[30:31]
	s_movk_i32 s2, 0x1600
	v_cvt_pk_bf16_f32 v135, v130, v131
	v_mad_i64_i32 v[136:137], s[26:27], v165, s2, v[128:129]
	v_lshlrev_b64 v[130:131], 1, v[174:175]
	v_lshl_add_u64 v[136:137], v[136:137], 0, v[130:131]
	global_store_dwordx4 v[136:137], v[132:135], off nt
	v_pk_fma_f32 v[66:67], v[66:67], v[166:167], v[82:83] op_sel_hi:[1,0,1]
	v_pk_fma_f32 v[62:63], v[62:63], v[164:165], v[94:95] op_sel_hi:[1,0,1]
	v_pk_mul_f32 v[132:133], v[124:125], s[88:89] op_sel_hi:[1,0]
	v_pk_mul_f32 v[124:125], v[126:127], s[88:89] op_sel_hi:[1,0]
	v_exp_f32_e32 v132, v132
	v_exp_f32_e32 v124, v124
	v_exp_f32_e32 v125, v125
	v_exp_f32_e32 v133, v133
	v_or_b32_e32 v134, 16, v165
	v_pk_mul_f32 v[66:67], v[74:75], v[66:67]
	v_pk_add_f32 v[124:125], v[124:125], 1.0 op_sel_hi:[1,0]
	v_pk_add_f32 v[132:133], v[132:133], 1.0 op_sel_hi:[1,0]
	v_rcp_f32_e32 v124, v124
	v_rcp_f32_e32 v125, v125
	v_rcp_f32_e32 v132, v132
	v_rcp_f32_e32 v133, v133
	v_pk_fma_f32 v[60:61], v[60:61], v[164:165], v[92:93] op_sel_hi:[1,0,1]
	v_pk_mul_f32 v[118:119], v[118:119], v[124:125]
	v_pk_mul_f32 v[124:125], v[120:121], s[88:89] op_sel_hi:[1,0]
	v_pk_mul_f32 v[116:117], v[116:117], v[132:133]
	v_exp_f32_e32 v124, v124
	v_exp_f32_e32 v125, v125
	v_pk_fma_f32 v[52:53], v[52:53], v[164:165], v[84:85] op_sel_hi:[1,0,1]
	v_pk_fma_f32 v[54:55], v[54:55], v[164:165], v[86:87] op_sel_hi:[1,0,1]
	v_pk_mul_f32 v[52:53], v[60:61], v[52:53]
	v_pk_add_f32 v[124:125], v[124:125], 1.0 op_sel_hi:[1,0]
	v_pk_fma_f32 v[56:57], v[56:57], v[164:165], v[88:89] op_sel_hi:[1,0,1]
	v_rcp_f32_e32 v124, v124
	v_rcp_f32_e32 v125, v125
	v_pk_mul_f32 v[54:55], v[62:63], v[54:55]
	v_pk_fma_f32 v[48:49], v[48:49], v[164:165], v[80:81] op_sel_hi:[1,0,1]
	v_pk_fma_f32 v[58:59], v[58:59], v[164:165], v[90:91] op_sel_hi:[1,0,1]
	v_pk_mul_f32 v[120:121], v[112:113], v[124:125]
	v_pk_mul_f32 v[112:113], v[122:123], s[88:89] op_sel_hi:[1,0]
	v_pk_mul_f32 v[48:49], v[56:57], v[48:49]
	v_exp_f32_e32 v112, v112
	v_exp_f32_e32 v113, v113
	v_pk_fma_f32 v[50:51], v[50:51], v[164:165], v[82:83] op_sel_hi:[1,0,1]
	v_pk_fma_f32 v[46:47], v[46:47], v[162:163], v[94:95] op_sel_hi:[1,0,1]
	v_pk_mul_f32 v[50:51], v[58:59], v[50:51]
	v_pk_add_f32 v[112:113], v[112:113], 1.0 op_sel_hi:[1,0]
	v_pk_fma_f32 v[44:45], v[44:45], v[162:163], v[92:93] op_sel_hi:[1,0,1]
	v_rcp_f32_e32 v112, v112
	v_rcp_f32_e32 v113, v113
	v_pk_fma_f32 v[36:37], v[36:37], v[162:163], v[84:85] op_sel_hi:[1,0,1]
	v_pk_fma_f32 v[38:39], v[38:39], v[162:163], v[86:87] op_sel_hi:[1,0,1]
	v_pk_mul_f32 v[36:37], v[44:45], v[36:37]
	v_pk_mul_f32 v[122:123], v[114:115], v[112:113]
	v_cvt_pk_bf16_f32 v112, v116, v117
	v_mad_i64_i32 v[116:117], s[26:27], v134, s2, v[128:129]
	v_cvt_pk_bf16_f32 v113, v118, v119
	v_lshl_add_u64 v[116:117], v[116:117], 0, v[130:131]
	v_cvt_pk_bf16_f32 v114, v120, v121
	v_cvt_pk_bf16_f32 v115, v122, v123
	global_store_dwordx4 v[116:117], v[112:115], off nt
	v_pk_fma_f32 v[40:41], v[40:41], v[162:163], v[88:89] op_sel_hi:[1,0,1]
	v_pk_mul_f32 v[38:39], v[46:47], v[38:39]
	v_pk_mul_f32 v[112:113], v[108:109], s[88:89] op_sel_hi:[1,0]
	v_pk_mul_f32 v[108:109], v[110:111], s[88:89] op_sel_hi:[1,0]
	v_exp_f32_e32 v112, v112
	v_exp_f32_e32 v108, v108
	v_exp_f32_e32 v109, v109
	v_exp_f32_e32 v113, v113
	v_or_b32_e32 v114, 32, v165
	v_pk_fma_f32 v[32:33], v[32:33], v[162:163], v[80:81] op_sel_hi:[1,0,1]
	v_pk_add_f32 v[108:109], v[108:109], 1.0 op_sel_hi:[1,0]
	v_pk_add_f32 v[112:113], v[112:113], 1.0 op_sel_hi:[1,0]
	v_rcp_f32_e32 v108, v108
	v_rcp_f32_e32 v109, v109
	v_rcp_f32_e32 v112, v112
	v_rcp_f32_e32 v113, v113
	v_pk_fma_f32 v[42:43], v[42:43], v[162:163], v[90:91] op_sel_hi:[1,0,1]
	v_pk_mul_f32 v[102:103], v[102:103], v[108:109]
	v_pk_mul_f32 v[108:109], v[104:105], s[88:89] op_sel_hi:[1,0]
	v_pk_mul_f32 v[100:101], v[100:101], v[112:113]
	v_exp_f32_e32 v108, v108
	v_exp_f32_e32 v109, v109
	v_pk_mul_f32 v[32:33], v[40:41], v[32:33]
	v_pk_add_f32 v[108:109], v[108:109], 1.0 op_sel_hi:[1,0]
	v_pk_fma_f32 v[34:35], v[34:35], v[162:163], v[82:83] op_sel_hi:[1,0,1]
	v_rcp_f32_e32 v108, v108
	v_rcp_f32_e32 v109, v109
	v_pk_mul_f32 v[34:35], v[42:43], v[34:35]
	v_pk_mul_f32 v[104:105], v[96:97], v[108:109]
	v_pk_mul_f32 v[96:97], v[106:107], s[88:89] op_sel_hi:[1,0]
	v_exp_f32_e32 v96, v96
	v_exp_f32_e32 v97, v97
	v_mov_b32_e32 v160, v214
	v_pk_fma_f32 v[30:31], v[30:31], v[160:161], v[94:95] op_sel_hi:[1,0,1]
	v_pk_fma_f32 v[28:29], v[28:29], v[160:161], v[92:93] op_sel_hi:[1,0,1]
	v_pk_add_f32 v[96:97], v[96:97], 1.0 op_sel_hi:[1,0]
	v_pk_fma_f32 v[20:21], v[20:21], v[160:161], v[84:85] op_sel_hi:[1,0,1]
	v_rcp_f32_e32 v96, v96
	v_rcp_f32_e32 v97, v97
	v_pk_mul_f32 v[20:21], v[28:29], v[20:21]
	v_pk_fma_f32 v[22:23], v[22:23], v[160:161], v[86:87] op_sel_hi:[1,0,1]
	v_pk_fma_f32 v[24:25], v[24:25], v[160:161], v[88:89] op_sel_hi:[1,0,1]
	v_pk_mul_f32 v[106:107], v[98:99], v[96:97]
	v_cvt_pk_bf16_f32 v96, v100, v101
	v_mad_i64_i32 v[100:101], s[26:27], v114, s2, v[128:129]
	v_cvt_pk_bf16_f32 v97, v102, v103
	v_lshl_add_u64 v[100:101], v[100:101], 0, v[130:131]
	v_cvt_pk_bf16_f32 v98, v104, v105
	v_cvt_pk_bf16_f32 v99, v106, v107
	global_store_dwordx4 v[100:101], v[96:99], off nt
; __device__ __forceinline__ unsigned cvt_pk_bf16(float lo, float hi) { unsigned r; asm volatile("v_cvt_pk_bf16_f32 %0, %1, %2" : "=v"(r) : "v"(lo), "v"(hi)); return r; }
;     __device__ __forceinline__ void operator()(const f32x4 (&acc)[2][2][4][2], const pg8::Unit& u, int wr, int wc, int fr_, int fq_) const {
;     ...
;                 const int lr = lrow0 + ai * 128 + m * 16;
;                 const float rs = rs8[ai * 4 + m];
;                 const f32x4 g0 = acc[ai][0][m][0] * rs + sv[0][0], g1 = acc[ai][0][m][1] * rs + sv[0][1];
;                 const f32x4 u0 = acc[ai][1][m][0] * rs + sv[1][0], u1 = acc[ai][1][m][1] * rs + sv[1][1];
;                 const f32x2 ha = pg8::silu_mul_pk((f32x2){g0[0], g0[1]}, (f32x2){u0[0], u0[1]}), hb = pg8::silu_mul_pk((f32x2){g0[2], g0[3]}, (f32x2){u0[2], u0[3]});
;                 const f32x2 hc = pg8::silu_mul_pk((f32x2){g1[0], g1[1]}, (f32x2){u1[0], u1[1]}), hd = pg8::silu_mul_pk((f32x2){g1[2], g1[3]}, (f32x2){u1[2], u1[3]});
;                 u32x4 w; w.x = cvt_pk_bf16(ha.x, ha.y); w.y = cvt_pk_bf16(hb.x, hb.y); w.z = cvt_pk_bf16(hc.x, hc.y); w.w = cvt_pk_bf16(hd.x, hd.y);
;                 *(u32x4*)(H + (size_t)lr * FF + hcol) = w;
	v_pk_mul_f32 v[22:23], v[30:31], v[22:23]
	v_pk_fma_f32 v[16:17], v[16:17], v[160:161], v[80:81] op_sel_hi:[1,0,1]
	v_pk_mul_f32 v[96:97], v[76:77], s[88:89] op_sel_hi:[1,0]
	v_pk_mul_f32 v[76:77], v[78:79], s[88:89] op_sel_hi:[1,0]
	v_exp_f32_e32 v96, v96
	v_exp_f32_e32 v76, v76
	v_exp_f32_e32 v77, v77
	v_exp_f32_e32 v97, v97
	v_or_b32_e32 v98, 48, v165
	v_pk_fma_f32 v[26:27], v[26:27], v[160:161], v[90:91] op_sel_hi:[1,0,1]
	v_pk_add_f32 v[76:77], v[76:77], 1.0 op_sel_hi:[1,0]
	v_pk_add_f32 v[96:97], v[96:97], 1.0 op_sel_hi:[1,0]
	v_rcp_f32_e32 v76, v76
	v_rcp_f32_e32 v77, v77
	v_rcp_f32_e32 v96, v96
	v_rcp_f32_e32 v97, v97
	v_pk_mul_f32 v[16:17], v[24:25], v[16:17]
	v_pk_mul_f32 v[70:71], v[70:71], v[76:77]
	v_pk_mul_f32 v[76:77], v[72:73], s[88:89] op_sel_hi:[1,0]
	v_pk_mul_f32 v[68:69], v[68:69], v[96:97]
	v_exp_f32_e32 v76, v76
	v_exp_f32_e32 v77, v77
	v_pk_fma_f32 v[18:19], v[18:19], v[160:161], v[82:83] op_sel_hi:[1,0,1]
	v_pk_add_f32 v[76:77], v[76:77], 1.0 op_sel_hi:[1,0]
	v_rcp_f32_e32 v76, v76
	v_rcp_f32_e32 v77, v77
	v_pk_mul_f32 v[18:19], v[26:27], v[18:19]
	v_pk_mul_f32 v[72:73], v[64:65], v[76:77]
	v_pk_mul_f32 v[64:65], v[74:75], s[88:89] op_sel_hi:[1,0]
	v_exp_f32_e32 v64, v64
	v_exp_f32_e32 v65, v65
	v_mov_b32_e32 v158, v215
	v_pk_fma_f32 v[14:15], v[14:15], v[158:159], v[94:95] op_sel_hi:[1,0,1]
	v_pk_fma_f32 v[12:13], v[12:13], v[158:159], v[92:93] op_sel_hi:[1,0,1]
	v_pk_add_f32 v[64:65], v[64:65], 1.0 op_sel_hi:[1,0]
	v_pk_fma_f32 v[4:5], v[4:5], v[158:159], v[84:85] op_sel_hi:[1,0,1]
	v_rcp_f32_e32 v64, v64
	v_rcp_f32_e32 v65, v65
	v_pk_mul_f32 v[4:5], v[12:13], v[4:5]
	v_pk_fma_f32 v[6:7], v[6:7], v[158:159], v[86:87] op_sel_hi:[1,0,1]
	v_pk_fma_f32 v[8:9], v[8:9], v[158:159], v[88:89] op_sel_hi:[1,0,1]
	v_pk_mul_f32 v[74:75], v[66:67], v[64:65]
	v_cvt_pk_bf16_f32 v64, v68, v69
	v_mad_i64_i32 v[68:69], s[26:27], v98, s2, v[128:129]
	v_cvt_pk_bf16_f32 v65, v70, v71
	v_lshl_add_u64 v[68:69], v[68:69], 0, v[130:131]
	v_cvt_pk_bf16_f32 v66, v72, v73
	v_cvt_pk_bf16_f32 v67, v74, v75
	global_store_dwordx4 v[68:69], v[64:67], off nt
	v_pk_mul_f32 v[6:7], v[14:15], v[6:7]
	v_pk_fma_f32 v[0:1], v[0:1], v[158:159], v[80:81] op_sel_hi:[1,0,1]
	v_pk_mul_f32 v[64:65], v[60:61], s[88:89] op_sel_hi:[1,0]
	v_pk_mul_f32 v[60:61], v[62:63], s[88:89] op_sel_hi:[1,0]
	v_exp_f32_e32 v64, v64
	v_exp_f32_e32 v60, v60
	v_exp_f32_e32 v61, v61
	v_exp_f32_e32 v65, v65
	v_add_u32_e32 v66, 0x80, v165
	v_pk_fma_f32 v[10:11], v[10:11], v[158:159], v[90:91] op_sel_hi:[1,0,1]
	v_pk_add_f32 v[60:61], v[60:61], 1.0 op_sel_hi:[1,0]
	v_pk_add_f32 v[64:65], v[64:65], 1.0 op_sel_hi:[1,0]
	v_rcp_f32_e32 v60, v60
	v_rcp_f32_e32 v61, v61
	v_rcp_f32_e32 v64, v64
	v_rcp_f32_e32 v65, v65
	v_pk_mul_f32 v[0:1], v[8:9], v[0:1]
	v_pk_mul_f32 v[54:55], v[54:55], v[60:61]
	v_pk_mul_f32 v[60:61], v[56:57], s[88:89] op_sel_hi:[1,0]
	v_pk_mul_f32 v[52:53], v[52:53], v[64:65]
	v_exp_f32_e32 v60, v60
	v_exp_f32_e32 v61, v61
	v_pk_fma_f32 v[2:3], v[2:3], v[158:159], v[82:83] op_sel_hi:[1,0,1]
	s_andn2_b64 vcc, exec, s[36:37]
	v_pk_mul_f32 v[2:3], v[10:11], v[2:3]
	v_pk_add_f32 v[60:61], v[60:61], 1.0 op_sel_hi:[1,0]
	s_nop 0
	v_rcp_f32_e32 v60, v60
	v_rcp_f32_e32 v61, v61
	s_nop 0
	v_pk_mul_f32 v[56:57], v[48:49], v[60:61]
	v_pk_mul_f32 v[48:49], v[58:59], s[88:89] op_sel_hi:[1,0]
	s_nop 0
	v_exp_f32_e32 v48, v48
	v_exp_f32_e32 v49, v49
	s_nop 0
	v_pk_add_f32 v[48:49], v[48:49], 1.0 op_sel_hi:[1,0]
	s_nop 0
	v_rcp_f32_e32 v48, v48
	v_rcp_f32_e32 v49, v49
	s_nop 0
	v_pk_mul_f32 v[58:59], v[50:51], v[48:49]
	v_cvt_pk_bf16_f32 v48, v52, v53
	v_mad_i64_i32 v[52:53], s[26:27], v66, s2, v[128:129]
	v_cvt_pk_bf16_f32 v49, v54, v55
	v_lshl_add_u64 v[52:53], v[52:53], 0, v[130:131]
	v_cvt_pk_bf16_f32 v50, v56, v57
	v_cvt_pk_bf16_f32 v51, v58, v59
	global_store_dwordx4 v[52:53], v[48:51], off nt
	s_nop 1
	v_pk_mul_f32 v[48:49], v[44:45], s[88:89] op_sel_hi:[1,0]
	v_pk_mul_f32 v[44:45], v[46:47], s[88:89] op_sel_hi:[1,0]
	v_exp_f32_e32 v48, v48
	v_exp_f32_e32 v44, v44
	v_exp_f32_e32 v45, v45
; __device__ __forceinline__ unsigned cvt_pk_bf16(float lo, float hi) { unsigned r; asm volatile("v_cvt_pk_bf16_f32 %0, %1, %2" : "=v"(r) : "v"(lo), "v"(hi)); return r; }
; template <class Epi, class Sched, bool ALIGN_EPI, bool SP2>
; __device__ __forceinline__ void gemm_phase(PG8_LAS unsigned char* lds, const Gemm g, const Sched& S, const Epi& E, int wid) {
;     ...
;         if (!has_next) break;
;     __device__ __forceinline__ void operator()(const f32x4 (&acc)[2][2][4][2], const pg8::Unit& u, int wr, int wc, int fr_, int fq_) const {
;     ...
;                 const int lr = lrow0 + ai * 128 + m * 16;
;                 const float rs = rs8[ai * 4 + m];
;                 const f32x4 g0 = acc[ai][0][m][0] * rs + sv[0][0], g1 = acc[ai][0][m][1] * rs + sv[0][1];
;                 const f32x4 u0 = acc[ai][1][m][0] * rs + sv[1][0], u1 = acc[ai][1][m][1] * rs + sv[1][1];
;                 const f32x2 ha = pg8::silu_mul_pk((f32x2){g0[0], g0[1]}, (f32x2){u0[0], u0[1]}), hb = pg8::silu_mul_pk((f32x2){g0[2], g0[3]}, (f32x2){u0[2], u0[3]});
;                 const f32x2 hc = pg8::silu_mul_pk((f32x2){g1[0], g1[1]}, (f32x2){u1[0], u1[1]}), hd = pg8::silu_mul_pk((f32x2){g1[2], g1[3]}, (f32x2){u1[2], u1[3]});
;                 u32x4 w; w.x = cvt_pk_bf16(ha.x, ha.y); w.y = cvt_pk_bf16(hb.x, hb.y); w.z = cvt_pk_bf16(hc.x, hc.y); w.w = cvt_pk_bf16(hd.x, hd.y);
;                 *(u32x4*)(H + (size_t)lr * FF + hcol) = w;
	v_exp_f32_e32 v49, v49
	v_add_u32_e32 v50, 0x90, v165
	v_pk_add_f32 v[44:45], v[44:45], 1.0 op_sel_hi:[1,0]
	s_nop 0
	v_rcp_f32_e32 v44, v44
	v_rcp_f32_e32 v45, v45
	v_pk_add_f32 v[48:49], v[48:49], 1.0 op_sel_hi:[1,0]
	v_pk_mul_f32 v[38:39], v[38:39], v[44:45]
	v_pk_mul_f32 v[44:45], v[40:41], s[88:89] op_sel_hi:[1,0]
	v_rcp_f32_e32 v48, v48
	v_exp_f32_e32 v44, v44
	v_exp_f32_e32 v45, v45
	v_rcp_f32_e32 v49, v49
	v_pk_add_f32 v[44:45], v[44:45], 1.0 op_sel_hi:[1,0]
	s_nop 0
	v_rcp_f32_e32 v44, v44
	v_rcp_f32_e32 v45, v45
	v_pk_mul_f32 v[36:37], v[36:37], v[48:49]
	v_pk_mul_f32 v[40:41], v[32:33], v[44:45]
	v_pk_mul_f32 v[32:33], v[42:43], s[88:89] op_sel_hi:[1,0]
	s_nop 0
	v_exp_f32_e32 v32, v32
	v_exp_f32_e32 v33, v33
	s_nop 0
	v_pk_add_f32 v[32:33], v[32:33], 1.0 op_sel_hi:[1,0]
	s_nop 0
	v_rcp_f32_e32 v32, v32
	v_rcp_f32_e32 v33, v33
	s_nop 0
	v_pk_mul_f32 v[42:43], v[34:35], v[32:33]
	v_cvt_pk_bf16_f32 v32, v36, v37
	v_mad_i64_i32 v[36:37], s[26:27], v50, s2, v[128:129]
	v_cvt_pk_bf16_f32 v33, v38, v39
	v_lshl_add_u64 v[36:37], v[36:37], 0, v[130:131]
	v_cvt_pk_bf16_f32 v34, v40, v41
	v_cvt_pk_bf16_f32 v35, v42, v43
	global_store_dwordx4 v[36:37], v[32:35], off nt
	s_nop 1
	v_pk_mul_f32 v[32:33], v[28:29], s[88:89] op_sel_hi:[1,0]
	v_pk_mul_f32 v[28:29], v[30:31], s[88:89] op_sel_hi:[1,0]
	v_exp_f32_e32 v32, v32
	v_exp_f32_e32 v28, v28
	v_exp_f32_e32 v29, v29
	v_exp_f32_e32 v33, v33
	v_add_u32_e32 v34, 0xa0, v165
	v_pk_add_f32 v[28:29], v[28:29], 1.0 op_sel_hi:[1,0]
	s_nop 0
	v_rcp_f32_e32 v28, v28
	v_rcp_f32_e32 v29, v29
	v_pk_add_f32 v[32:33], v[32:33], 1.0 op_sel_hi:[1,0]
	v_pk_mul_f32 v[22:23], v[22:23], v[28:29]
	v_pk_mul_f32 v[28:29], v[24:25], s[88:89] op_sel_hi:[1,0]
	v_rcp_f32_e32 v32, v32
	v_exp_f32_e32 v28, v28
	v_exp_f32_e32 v29, v29
	v_rcp_f32_e32 v33, v33
	v_pk_add_f32 v[28:29], v[28:29], 1.0 op_sel_hi:[1,0]
	s_nop 0
	v_rcp_f32_e32 v28, v28
	v_rcp_f32_e32 v29, v29
	v_pk_mul_f32 v[20:21], v[20:21], v[32:33]
	v_pk_mul_f32 v[24:25], v[16:17], v[28:29]
	v_pk_mul_f32 v[16:17], v[26:27], s[88:89] op_sel_hi:[1,0]
	s_nop 0
	v_exp_f32_e32 v16, v16
	v_exp_f32_e32 v17, v17
	s_nop 0
	v_pk_add_f32 v[16:17], v[16:17], 1.0 op_sel_hi:[1,0]
	s_nop 0
	v_rcp_f32_e32 v16, v16
	v_rcp_f32_e32 v17, v17
	s_nop 0
	v_pk_mul_f32 v[26:27], v[18:19], v[16:17]
	v_cvt_pk_bf16_f32 v16, v20, v21
	v_mad_i64_i32 v[20:21], s[26:27], v34, s2, v[128:129]
	v_cvt_pk_bf16_f32 v17, v22, v23
	v_lshl_add_u64 v[20:21], v[20:21], 0, v[130:131]
	v_cvt_pk_bf16_f32 v18, v24, v25
	v_cvt_pk_bf16_f32 v19, v26, v27
	global_store_dwordx4 v[20:21], v[16:19], off nt
	s_nop 1
	v_pk_mul_f32 v[16:17], v[12:13], s[88:89] op_sel_hi:[1,0]
	v_pk_mul_f32 v[12:13], v[14:15], s[88:89] op_sel_hi:[1,0]
	v_exp_f32_e32 v16, v16
	v_exp_f32_e32 v12, v12
	v_exp_f32_e32 v13, v13
	v_exp_f32_e32 v17, v17
	v_add_u32_e32 v18, 0xb0, v165
	v_pk_add_f32 v[12:13], v[12:13], 1.0 op_sel_hi:[1,0]
	s_nop 0
	v_rcp_f32_e32 v12, v12
	v_rcp_f32_e32 v13, v13
	v_pk_add_f32 v[16:17], v[16:17], 1.0 op_sel_hi:[1,0]
	v_pk_mul_f32 v[6:7], v[6:7], v[12:13]
	v_pk_mul_f32 v[12:13], v[8:9], s[88:89] op_sel_hi:[1,0]
	v_rcp_f32_e32 v16, v16
	v_exp_f32_e32 v12, v12
	v_exp_f32_e32 v13, v13
	v_rcp_f32_e32 v17, v17
	v_pk_add_f32 v[12:13], v[12:13], 1.0 op_sel_hi:[1,0]
	s_nop 0
	v_rcp_f32_e32 v12, v12
	v_rcp_f32_e32 v13, v13
	v_pk_mul_f32 v[4:5], v[4:5], v[16:17]
	v_pk_mul_f32 v[8:9], v[0:1], v[12:13]
	v_pk_mul_f32 v[0:1], v[10:11], s[88:89] op_sel_hi:[1,0]
	s_nop 0
	v_exp_f32_e32 v0, v0
	v_exp_f32_e32 v1, v1
	s_nop 0
	v_pk_add_f32 v[0:1], v[0:1], 1.0 op_sel_hi:[1,0]
	s_nop 0
	v_rcp_f32_e32 v0, v0
	v_rcp_f32_e32 v1, v1
	s_nop 0
	v_pk_mul_f32 v[10:11], v[2:3], v[0:1]
	v_cvt_pk_bf16_f32 v0, v4, v5
	v_mad_i64_i32 v[4:5], s[26:27], v18, s2, v[128:129]
	v_lshl_add_u64 v[4:5], v[4:5], 0, v[130:131]
	s_mov_b64 s[26:27], -1
	v_cvt_pk_bf16_f32 v1, v6, v7
	v_cvt_pk_bf16_f32 v2, v8, v9
	v_cvt_pk_bf16_f32 v3, v10, v11
	global_store_dwordx4 v[4:5], v[0:3], off nt
	s_cbranch_vccnz .LBB0_369
	s_and_b64 vcc, exec, s[34:35]
	s_cbranch_vccnz .LBB0_368
	s_branch .LBB0_368
